# gate GEMM epilogue: all 16 E loads issued up front, counted vmcnt, packed mul/add
# speedup vs baseline: 1.0050x; 1.0050x over previous
; __device__ __forceinline__ unsigned pk2(float lo, float hi) { f32x2_t v = {lo, hi}; bf16x2_t b = __builtin_convertvector(v, bf16x2_t); return __builtin_bit_cast(unsigned, b); }
; __device__ __forceinline__ float bflo(unsigned u) { return __uint_as_float(u << 16); }
; __device__ __forceinline__ float bfhi(unsigned u) { return __uint_as_float(u & 0xffff0000u); }
; __device__ __forceinline__ float fast_sigmoid(float z) { return __builtin_amdgcn_rcpf(1.0f + __builtin_amdgcn_exp2f(-1.4426950408889634f * z)); }
;     __device__ __forceinline__ void operator()(const f32x4 (&acc)[2][2][4][2], const Unit& u, int wr, int wc, int fr, int fq) const {
;         const int row0 = u.pm * BM + wr * 64 + fr; const int col0 = u.pn * BM + wc * 32 + 8 * fq;
; #pragma unroll
;         for (int ai = 0; ai < 2; ++ai)
; #pragma unroll
;             for (int m = 0; m < 4; ++m) {
;                 const size_t ro = (size_t)(row0 + ai * HALF + m * 16) * ldc + col0;
; #pragma unroll
;                 for (int bj = 0; bj < 2; ++bj) {
;                     f32x4 v0 = acc[ai][bj][m][0], v1 = acc[ai][bj][m][1];
;                     if (mode == 1) {
;                         const u32x4 e = *(const u32x4*)(E + ro + bj * HALF);
;                         v0[0] = fast_sigmoid(v0[0]) * bflo(e.x); v0[1] = fast_sigmoid(v0[1]) * bfhi(e.x); v0[2] = fast_sigmoid(v0[2]) * bflo(e.y); v0[3] = fast_sigmoid(v0[3]) * bfhi(e.y);
;                         v1[0] = fast_sigmoid(v1[0]) * bflo(e.z); v1[1] = fast_sigmoid(v1[1]) * bfhi(e.z); v1[2] = fast_sigmoid(v1[2]) * bflo(e.w); v1[3] = fast_sigmoid(v1[3]) * bfhi(e.w);
;                     }
;                     u32x4 w; w.x = pk2(v0[0], v0[1]); w.y = pk2(v0[2], v0[3]); w.z = pk2(v1[0], v1[1]); w.w = pk2(v1[2], v1[3]);
;                     *(u32x4*)(O + ro + bj * HALF) = w;
;                 }
;             }
;     }
.LBB0_536:
	v_readlane_b32 s2, v254, 44
	v_readlane_b32 s3, v254, 45
	s_nop 0
	s_and_b64 vcc, exec, s[2:3]
	s_cbranch_vccnz .Lgate_epi
	v_lshl_or_b32 v140, s28, 8, v193
	v_lshl_add_u32 v146, s90, 8, v191
	v_ashrrev_i32_e32 v141, 31, v140
	v_mad_u64_u32 v[142:143], s[2:3], s0, v146, v[140:141]
	v_ashrrev_i32_e32 v130, 31, v146
	v_readlane_b32 s2, v254, 44
	v_mul_lo_u32 v147, s0, v130
	v_mul_lo_u32 v130, s1, v146
	v_readlane_b32 s3, v254, 45
	v_add3_u32 v143, v130, v143, v147
	s_andn2_b64 vcc, exec, s[2:3]
	v_cndmask_b32_e64 v130, 0, 1, s[2:3]
	v_readlane_b32 s2, v254, 52
	v_cmp_ne_u32_e64 s[60:61], 1, v130
	v_readlane_b32 s3, v254, 53
	v_mov_b64_e32 v[132:133], v[120:121]
	v_mov_b64_e32 v[138:139], v[112:113]
	v_lshl_add_u64 v[144:145], v[142:143], 1, s[2:3]
	v_mov_b64_e32 v[130:131], v[118:119]
	v_mov_b64_e32 v[136:137], v[110:111]
.LBB0_538:
	v_cvt_pk_bf16_f32 v130, v130, v131
	v_cvt_pk_bf16_f32 v131, v132, v133
	v_cvt_pk_bf16_f32 v132, v136, v137
	v_cvt_pk_bf16_f32 v133, v138, v139
	v_lshl_add_u64 v[142:143], v[142:143], 1, s[10:11]
	global_store_dwordx4 v[142:143], v[130:133], off
	v_mov_b64_e32 v[138:139], v[124:125]
	s_and_b64 vcc, exec, s[60:61]
	v_mov_b64_e32 v[132:133], v[128:129]
	v_mov_b64_e32 v[130:131], v[126:127]
	v_mov_b64_e32 v[136:137], v[122:123]
.LBB0_540:
	v_cvt_pk_bf16_f32 v130, v130, v131
	v_cvt_pk_bf16_f32 v131, v132, v133
	v_cvt_pk_bf16_f32 v132, v136, v137
	v_cvt_pk_bf16_f32 v133, v138, v139
	global_store_dwordx4 v[142:143], v[130:133], off offset:256
	v_mov_b64_e32 v[138:139], v[96:97]
	s_and_b64 vcc, exec, s[60:61]
	v_or_b32_e32 v130, 16, v146
	v_mad_u64_u32 v[144:145], s[2:3], s0, v130, v[140:141]
	v_mul_lo_u32 v131, s1, v130
	v_readlane_b32 s2, v254, 52
	v_add3_u32 v145, v131, v145, v147
	v_readlane_b32 s3, v254, 53
	v_mov_b64_e32 v[132:133], v[104:105]
	v_mov_b64_e32 v[130:131], v[102:103]
	v_lshl_add_u64 v[142:143], v[144:145], 1, s[2:3]
	v_mov_b64_e32 v[136:137], v[94:95]
.LBB0_542:
	v_cvt_pk_bf16_f32 v130, v130, v131
	v_cvt_pk_bf16_f32 v131, v132, v133
	v_cvt_pk_bf16_f32 v132, v136, v137
	v_cvt_pk_bf16_f32 v133, v138, v139
	v_lshl_add_u64 v[144:145], v[144:145], 1, s[10:11]
	global_store_dwordx4 v[144:145], v[130:133], off
	v_mov_b64_e32 v[138:139], v[108:109]
	s_and_b64 vcc, exec, s[60:61]
	v_mov_b64_e32 v[132:133], v[116:117]
	v_mov_b64_e32 v[130:131], v[114:115]
	v_mov_b64_e32 v[136:137], v[106:107]
.LBB0_544:
	v_cvt_pk_bf16_f32 v130, v130, v131
	v_cvt_pk_bf16_f32 v131, v132, v133
	v_cvt_pk_bf16_f32 v132, v136, v137
	v_cvt_pk_bf16_f32 v133, v138, v139
	global_store_dwordx4 v[144:145], v[130:133], off offset:256
	v_mov_b64_e32 v[138:139], v[76:77]
	s_and_b64 vcc, exec, s[60:61]
	v_or_b32_e32 v130, 32, v146
	v_mad_u64_u32 v[144:145], s[2:3], s0, v130, v[140:141]
	v_mul_lo_u32 v131, s1, v130
	v_readlane_b32 s2, v254, 52
	v_add3_u32 v145, v131, v145, v147
	v_readlane_b32 s3, v254, 53
	v_mov_b64_e32 v[132:133], v[88:89]
	v_mov_b64_e32 v[130:131], v[86:87]
	v_lshl_add_u64 v[142:143], v[144:145], 1, s[2:3]
	v_mov_b64_e32 v[136:137], v[74:75]
.LBB0_546:
	v_cvt_pk_bf16_f32 v130, v130, v131
	v_cvt_pk_bf16_f32 v131, v132, v133
	v_cvt_pk_bf16_f32 v132, v136, v137
	v_cvt_pk_bf16_f32 v133, v138, v139
	v_lshl_add_u64 v[144:145], v[144:145], 1, s[10:11]
	global_store_dwordx4 v[144:145], v[130:133], off
	v_mov_b64_e32 v[138:139], v[92:93]
	s_and_b64 vcc, exec, s[60:61]
	v_mov_b64_e32 v[132:133], v[100:101]
	v_mov_b64_e32 v[130:131], v[98:99]
	v_mov_b64_e32 v[136:137], v[90:91]
.LBB0_548:
	v_cvt_pk_bf16_f32 v130, v130, v131
	v_cvt_pk_bf16_f32 v131, v132, v133
	v_cvt_pk_bf16_f32 v132, v136, v137
	v_cvt_pk_bf16_f32 v133, v138, v139
	global_store_dwordx4 v[144:145], v[130:133], off offset:256
	v_mov_b64_e32 v[138:139], v[72:73]
	s_and_b64 vcc, exec, s[60:61]
	v_or_b32_e32 v130, 48, v146
	v_mad_u64_u32 v[144:145], s[2:3], s0, v130, v[140:141]
	v_mul_lo_u32 v131, s1, v130
	v_readlane_b32 s2, v254, 52
	v_add3_u32 v145, v131, v145, v147
	v_readlane_b32 s3, v254, 53
	v_mov_b64_e32 v[132:133], v[84:85]
	v_mov_b64_e32 v[130:131], v[82:83]
	v_lshl_add_u64 v[142:143], v[144:145], 1, s[2:3]
	v_mov_b64_e32 v[136:137], v[70:71]
.LBB0_550:
	v_cvt_pk_bf16_f32 v130, v130, v131
	v_cvt_pk_bf16_f32 v131, v132, v133
	v_cvt_pk_bf16_f32 v132, v136, v137
	v_cvt_pk_bf16_f32 v133, v138, v139
	v_lshl_add_u64 v[144:145], v[144:145], 1, s[10:11]
	global_store_dwordx4 v[144:145], v[130:133], off
	v_mov_b64_e32 v[138:139], v[68:69]
	s_and_b64 vcc, exec, s[60:61]
	v_mov_b64_e32 v[132:133], v[80:81]
	v_mov_b64_e32 v[130:131], v[78:79]
	v_mov_b64_e32 v[136:137], v[66:67]
.LBB0_552:
	v_cvt_pk_bf16_f32 v130, v130, v131
	v_cvt_pk_bf16_f32 v131, v132, v133
	v_cvt_pk_bf16_f32 v132, v136, v137
	v_cvt_pk_bf16_f32 v133, v138, v139
	global_store_dwordx4 v[144:145], v[130:133], off offset:256
	v_mov_b64_e32 v[138:139], v[48:49]
	s_and_b64 vcc, exec, s[60:61]
	v_add_u32_e32 v130, 0x80, v146
	v_ashrrev_i32_e32 v131, 31, v130
	v_mad_u64_u32 v[144:145], s[2:3], s0, v130, v[140:141]
	v_mul_lo_u32 v131, s0, v131
	v_mul_lo_u32 v132, s1, v130
	v_readlane_b32 s2, v254, 52
	v_add3_u32 v145, v132, v145, v131
	v_readlane_b32 s3, v254, 53
	v_mov_b64_e32 v[132:133], v[56:57]
	v_mov_b64_e32 v[130:131], v[54:55]
	v_lshl_add_u64 v[142:143], v[144:145], 1, s[2:3]
	v_mov_b64_e32 v[136:137], v[46:47]
.LBB0_554:
	v_cvt_pk_bf16_f32 v130, v130, v131
	v_cvt_pk_bf16_f32 v131, v132, v133
	v_cvt_pk_bf16_f32 v132, v136, v137
	v_cvt_pk_bf16_f32 v133, v138, v139
	v_lshl_add_u64 v[144:145], v[144:145], 1, s[10:11]
	global_store_dwordx4 v[144:145], v[130:133], off
	v_mov_b64_e32 v[138:139], v[60:61]
	s_and_b64 vcc, exec, s[60:61]
	v_mov_b64_e32 v[132:133], v[64:65]
	v_mov_b64_e32 v[130:131], v[62:63]
	v_mov_b64_e32 v[136:137], v[58:59]
; __device__ __forceinline__ unsigned pk2(float lo, float hi) { f32x2_t v = {lo, hi}; bf16x2_t b = __builtin_convertvector(v, bf16x2_t); return __builtin_bit_cast(unsigned, b); }
; __device__ __forceinline__ float bflo(unsigned u) { return __uint_as_float(u << 16); }
; __device__ __forceinline__ float bfhi(unsigned u) { return __uint_as_float(u & 0xffff0000u); }
; __device__ __forceinline__ float fast_sigmoid(float z) { return __builtin_amdgcn_rcpf(1.0f + __builtin_amdgcn_exp2f(-1.4426950408889634f * z)); }
;     __device__ __forceinline__ void operator()(const f32x4 (&acc)[2][2][4][2], const Unit& u, int wr, int wc, int fr, int fq) const {
;         const int row0 = u.pm * BM + wr * 64 + fr; const int col0 = u.pn * BM + wc * 32 + 8 * fq;
; #pragma unroll
;         for (int ai = 0; ai < 2; ++ai)
; #pragma unroll
;             for (int m = 0; m < 4; ++m) {
;                 const size_t ro = (size_t)(row0 + ai * HALF + m * 16) * ldc + col0;
; #pragma unroll
;                 for (int bj = 0; bj < 2; ++bj) {
;                     f32x4 v0 = acc[ai][bj][m][0], v1 = acc[ai][bj][m][1];
;                     if (mode == 1) {
;                         const u32x4 e = *(const u32x4*)(E + ro + bj * HALF);
;                         v0[0] = fast_sigmoid(v0[0]) * bflo(e.x); v0[1] = fast_sigmoid(v0[1]) * bfhi(e.x); v0[2] = fast_sigmoid(v0[2]) * bflo(e.y); v0[3] = fast_sigmoid(v0[3]) * bfhi(e.y);
;                         v1[0] = fast_sigmoid(v1[0]) * bflo(e.z); v1[1] = fast_sigmoid(v1[1]) * bfhi(e.z); v1[2] = fast_sigmoid(v1[2]) * bflo(e.w); v1[3] = fast_sigmoid(v1[3]) * bfhi(e.w);
;                     }
;                     u32x4 w; w.x = pk2(v0[0], v0[1]); w.y = pk2(v0[2], v0[3]); w.z = pk2(v1[0], v1[1]); w.w = pk2(v1[2], v1[3]);
;                     *(u32x4*)(O + ro + bj * HALF) = w;
.LBB0_556:
	v_cvt_pk_bf16_f32 v130, v130, v131
	v_cvt_pk_bf16_f32 v131, v132, v133
	v_cvt_pk_bf16_f32 v132, v136, v137
	v_cvt_pk_bf16_f32 v133, v138, v139
	global_store_dwordx4 v[144:145], v[130:133], off offset:256
	v_mov_b64_e32 v[138:139], v[32:33]
	s_and_b64 vcc, exec, s[60:61]
	v_add_u32_e32 v130, 0x90, v146
	v_ashrrev_i32_e32 v131, 31, v130
	v_mad_u64_u32 v[144:145], s[2:3], s0, v130, v[140:141]
	v_mul_lo_u32 v131, s0, v131
	v_mul_lo_u32 v132, s1, v130
	v_readlane_b32 s2, v254, 52
	v_add3_u32 v145, v132, v145, v131
	v_readlane_b32 s3, v254, 53
	v_mov_b64_e32 v[132:133], v[40:41]
	v_mov_b64_e32 v[130:131], v[38:39]
	v_lshl_add_u64 v[142:143], v[144:145], 1, s[2:3]
	v_mov_b64_e32 v[136:137], v[30:31]
.LBB0_558:
	v_cvt_pk_bf16_f32 v130, v130, v131
	v_cvt_pk_bf16_f32 v131, v132, v133
	v_cvt_pk_bf16_f32 v132, v136, v137
	v_cvt_pk_bf16_f32 v133, v138, v139
	v_lshl_add_u64 v[144:145], v[144:145], 1, s[10:11]
	global_store_dwordx4 v[144:145], v[130:133], off
	v_mov_b64_e32 v[138:139], v[44:45]
	s_and_b64 vcc, exec, s[60:61]
	v_mov_b64_e32 v[132:133], v[52:53]
	v_mov_b64_e32 v[130:131], v[50:51]
	v_mov_b64_e32 v[136:137], v[42:43]
.LBB0_560:
	v_cvt_pk_bf16_f32 v130, v130, v131
	v_cvt_pk_bf16_f32 v131, v132, v133
	v_cvt_pk_bf16_f32 v132, v136, v137
	v_cvt_pk_bf16_f32 v133, v138, v139
	global_store_dwordx4 v[144:145], v[130:133], off offset:256
	v_mov_b64_e32 v[138:139], v[20:21]
	s_and_b64 vcc, exec, s[60:61]
	v_add_u32_e32 v130, 0xa0, v146
	v_ashrrev_i32_e32 v131, 31, v130
	v_mad_u64_u32 v[144:145], s[2:3], s0, v130, v[140:141]
	v_mul_lo_u32 v131, s0, v131
	v_mul_lo_u32 v132, s1, v130
	v_readlane_b32 s2, v254, 52
	v_add3_u32 v145, v132, v145, v131
	v_readlane_b32 s3, v254, 53
	v_mov_b64_e32 v[132:133], v[24:25]
	v_mov_b64_e32 v[130:131], v[22:23]
	v_lshl_add_u64 v[142:143], v[144:145], 1, s[2:3]
	v_mov_b64_e32 v[136:137], v[18:19]
.LBB0_562:
	v_cvt_pk_bf16_f32 v130, v130, v131
	v_cvt_pk_bf16_f32 v131, v132, v133
	v_cvt_pk_bf16_f32 v132, v136, v137
	v_cvt_pk_bf16_f32 v133, v138, v139
	v_lshl_add_u64 v[144:145], v[144:145], 1, s[10:11]
	global_store_dwordx4 v[144:145], v[130:133], off
	v_mov_b64_e32 v[138:139], v[28:29]
	s_and_b64 vcc, exec, s[60:61]
	v_mov_b64_e32 v[132:133], v[36:37]
	v_mov_b64_e32 v[130:131], v[34:35]
	v_mov_b64_e32 v[136:137], v[26:27]
.LBB0_564:
	v_cvt_pk_bf16_f32 v130, v130, v131
	v_cvt_pk_bf16_f32 v131, v132, v133
	v_cvt_pk_bf16_f32 v132, v136, v137
	v_cvt_pk_bf16_f32 v133, v138, v139
	global_store_dwordx4 v[144:145], v[130:133], off offset:256
	v_mov_b64_e32 v[138:139], v[8:9]
	s_and_b64 vcc, exec, s[60:61]
	v_add_u32_e32 v130, 0xb0, v146
	v_ashrrev_i32_e32 v131, 31, v130
	v_mad_u64_u32 v[142:143], s[2:3], s0, v130, v[140:141]
	v_mul_lo_u32 v131, s0, v131
	v_mul_lo_u32 v132, s1, v130
	v_readlane_b32 s2, v254, 52
	v_add3_u32 v143, v132, v143, v131
	v_readlane_b32 s3, v254, 53
	v_mov_b64_e32 v[132:133], v[16:17]
	v_mov_b64_e32 v[130:131], v[14:15]
	v_lshl_add_u64 v[140:141], v[142:143], 1, s[2:3]
	v_mov_b64_e32 v[136:137], v[6:7]
.LBB0_566:
	v_cvt_pk_bf16_f32 v130, v130, v131
	v_cvt_pk_bf16_f32 v131, v132, v133
	v_cvt_pk_bf16_f32 v132, v136, v137
	v_cvt_pk_bf16_f32 v133, v138, v139
	v_lshl_add_u64 v[142:143], v[142:143], 1, s[10:11]
	global_store_dwordx4 v[142:143], v[130:133], off
	v_mov_b64_e32 v[138:139], v[4:5]
	s_and_b64 vcc, exec, s[60:61]
	v_mov_b64_e32 v[132:133], v[12:13]
	v_mov_b64_e32 v[130:131], v[10:11]
	v_mov_b64_e32 v[136:137], v[2:3]
.LBB0_568:
	v_cvt_pk_bf16_f32 v130, v130, v131
	v_cvt_pk_bf16_f32 v131, v132, v133
	v_cvt_pk_bf16_f32 v132, v136, v137
	v_cvt_pk_bf16_f32 v133, v138, v139
	global_store_dwordx4 v[142:143], v[130:133], off offset:256
	s_branch .LBB0_535
.Lgate_epi:
	v_lshl_or_b32 v140, s28, 8, v193
	v_lshl_add_u32 v146, s90, 8, v191
	v_readlane_b32 s2, v254, 52
	v_readlane_b32 s3, v254, 53
	v_lshlrev_b32_e32 v141, 11, v146
	v_lshl_add_u32 v141, v140, 1, v141
	s_mov_b32 s60, 0xbfb8aa3b
	s_mov_b32 s61, 0xbfb8aa3b
	s_mov_b32 s4, 1.0
	s_mov_b32 s5, 1.0
	s_nop 1
	global_load_dwordx4 v[148:151], v141, s[2:3]
	global_load_dwordx4 v[152:155], v141, s[2:3] offset:256
	v_add_u32_e32 v147, 0x8000, v141
	global_load_dwordx4 v[156:159], v147, s[2:3]
	global_load_dwordx4 v[160:163], v147, s[2:3] offset:256
	v_add_u32_e32 v147, 0x10000, v141
	global_load_dwordx4 v[164:167], v147, s[2:3]
	global_load_dwordx4 v[168:171], v147, s[2:3] offset:256
	v_add_u32_e32 v147, 0x18000, v141
	global_load_dwordx4 v[172:175], v147, s[2:3]
	global_load_dwordx4 v[220:223], v147, s[2:3] offset:256
	v_add_u32_e32 v147, 0x40000, v141
	global_load_dwordx4 v[224:227], v147, s[2:3]
	global_load_dwordx4 v[228:231], v147, s[2:3] offset:256
	v_add_u32_e32 v147, 0x48000, v141
	global_load_dwordx4 v[232:235], v147, s[2:3]
	global_load_dwordx4 v[236:239], v147, s[2:3] offset:256
	v_add_u32_e32 v147, 0x50000, v141
	global_load_dwordx4 v[240:243], v147, s[2:3]
	global_load_dwordx4 v[244:247], v147, s[2:3] offset:256
	v_add_u32_e32 v147, 0x58000, v141
	global_load_dwordx4 v[248:251], v147, s[2:3]
	global_load_dwordx2 v[176:177], v147, s[2:3] offset:256
	global_load_dwordx2 v[188:189], v147, s[2:3] offset:264
	s_waitcnt vmcnt(16)
; __device__ __forceinline__ unsigned pk2(float lo, float hi) { f32x2_t v = {lo, hi}; bf16x2_t b = __builtin_convertvector(v, bf16x2_t); return __builtin_bit_cast(unsigned, b); }
; __device__ __forceinline__ float bflo(unsigned u) { return __uint_as_float(u << 16); }
; __device__ __forceinline__ float bfhi(unsigned u) { return __uint_as_float(u & 0xffff0000u); }
; __device__ __forceinline__ float fast_sigmoid(float z) { return __builtin_amdgcn_rcpf(1.0f + __builtin_amdgcn_exp2f(-1.4426950408889634f * z)); }
;     __device__ __forceinline__ void operator()(const f32x4 (&acc)[2][2][4][2], const Unit& u, int wr, int wc, int fr, int fq) const {
;     ...
;                     if (mode == 1) {
;                         const u32x4 e = *(const u32x4*)(E + ro + bj * HALF);
;                         v0[0] = fast_sigmoid(v0[0]) * bflo(e.x); v0[1] = fast_sigmoid(v0[1]) * bfhi(e.x); v0[2] = fast_sigmoid(v0[2]) * bflo(e.y); v0[3] = fast_sigmoid(v0[3]) * bfhi(e.y);
;                         v1[0] = fast_sigmoid(v1[0]) * bflo(e.z); v1[1] = fast_sigmoid(v1[1]) * bfhi(e.z); v1[2] = fast_sigmoid(v1[2]) * bflo(e.w); v1[3] = fast_sigmoid(v1[3]) * bfhi(e.w);
;                     }
;                     u32x4 w; w.x = pk2(v0[0], v0[1]); w.y = pk2(v0[2], v0[3]); w.z = pk2(v1[0], v1[1]); w.w = pk2(v1[2], v1[3]);
;                     *(u32x4*)(O + ro + bj * HALF) = w;
	v_lshlrev_b32_e32 v138, 16, v148
	v_and_b32_e32 v139, 0xffff0000, v148
	v_lshlrev_b32_e32 v142, 16, v149
	v_and_b32_e32 v143, 0xffff0000, v149
	v_lshlrev_b32_e32 v144, 16, v150
	v_and_b32_e32 v145, 0xffff0000, v150
	v_lshlrev_b32_e32 v146, 16, v151
	v_and_b32_e32 v147, 0xffff0000, v151
	v_pk_mul_f32 v[130:131], v[118:119], s[60:61]
	v_pk_mul_f32 v[132:133], v[120:121], s[60:61]
	v_pk_mul_f32 v[134:135], v[110:111], s[60:61]
	v_pk_mul_f32 v[136:137], v[112:113], s[60:61]
	v_exp_f32_e32 v130, v130
	v_exp_f32_e32 v131, v131
	v_exp_f32_e32 v132, v132
	v_exp_f32_e32 v133, v133
	v_exp_f32_e32 v134, v134
	v_exp_f32_e32 v135, v135
	v_exp_f32_e32 v136, v136
	v_exp_f32_e32 v137, v137
	v_pk_add_f32 v[130:131], v[130:131], s[4:5]
	v_pk_add_f32 v[132:133], v[132:133], s[4:5]
	v_pk_add_f32 v[134:135], v[134:135], s[4:5]
	v_pk_add_f32 v[136:137], v[136:137], s[4:5]
	v_rcp_f32_e32 v130, v130
	v_rcp_f32_e32 v131, v131
	v_rcp_f32_e32 v132, v132
	v_rcp_f32_e32 v133, v133
	v_rcp_f32_e32 v134, v134
	v_rcp_f32_e32 v135, v135
	v_rcp_f32_e32 v136, v136
	v_rcp_f32_e32 v137, v137
	v_add_u32_e32 v140, 0x0, v141
	v_pk_mul_f32 v[130:131], v[130:131], v[138:139]
	v_pk_mul_f32 v[132:133], v[132:133], v[142:143]
	v_pk_mul_f32 v[134:135], v[134:135], v[144:145]
	v_pk_mul_f32 v[136:137], v[136:137], v[146:147]
	v_cvt_pk_bf16_f32 v130, v130, v131
	v_cvt_pk_bf16_f32 v131, v132, v133
	v_cvt_pk_bf16_f32 v132, v134, v135
	v_cvt_pk_bf16_f32 v133, v136, v137
	global_store_dwordx4 v140, v[130:133], s[10:11]
	s_waitcnt vmcnt(16)
	v_lshlrev_b32_e32 v138, 16, v152
	v_and_b32_e32 v139, 0xffff0000, v152
	v_lshlrev_b32_e32 v142, 16, v153
	v_and_b32_e32 v143, 0xffff0000, v153
	v_lshlrev_b32_e32 v144, 16, v154
	v_and_b32_e32 v145, 0xffff0000, v154
	v_lshlrev_b32_e32 v146, 16, v155
	v_and_b32_e32 v147, 0xffff0000, v155
	v_pk_mul_f32 v[130:131], v[126:127], s[60:61]
	v_pk_mul_f32 v[132:133], v[128:129], s[60:61]
	v_pk_mul_f32 v[134:135], v[122:123], s[60:61]
	v_pk_mul_f32 v[136:137], v[124:125], s[60:61]
	v_exp_f32_e32 v130, v130
	v_exp_f32_e32 v131, v131
	v_exp_f32_e32 v132, v132
	v_exp_f32_e32 v133, v133
	v_exp_f32_e32 v134, v134
	v_exp_f32_e32 v135, v135
	v_exp_f32_e32 v136, v136
	v_exp_f32_e32 v137, v137
	v_pk_add_f32 v[130:131], v[130:131], s[4:5]
	v_pk_add_f32 v[132:133], v[132:133], s[4:5]
	v_pk_add_f32 v[134:135], v[134:135], s[4:5]
	v_pk_add_f32 v[136:137], v[136:137], s[4:5]
	v_rcp_f32_e32 v130, v130
	v_rcp_f32_e32 v131, v131
	v_rcp_f32_e32 v132, v132
	v_rcp_f32_e32 v133, v133
	v_rcp_f32_e32 v134, v134
	v_rcp_f32_e32 v135, v135
	v_rcp_f32_e32 v136, v136
	v_rcp_f32_e32 v137, v137
	v_add_u32_e32 v140, 0x0, v141
	v_pk_mul_f32 v[130:131], v[130:131], v[138:139]
	v_pk_mul_f32 v[132:133], v[132:133], v[142:143]
	v_pk_mul_f32 v[134:135], v[134:135], v[144:145]
	v_pk_mul_f32 v[136:137], v[136:137], v[146:147]
	v_cvt_pk_bf16_f32 v130, v130, v131
	v_cvt_pk_bf16_f32 v131, v132, v133
	v_cvt_pk_bf16_f32 v132, v134, v135
	v_cvt_pk_bf16_f32 v133, v136, v137
	global_store_dwordx4 v140, v[130:133], s[10:11] offset:256
	s_waitcnt vmcnt(16)
	v_lshlrev_b32_e32 v138, 16, v156
	v_and_b32_e32 v139, 0xffff0000, v156
	v_lshlrev_b32_e32 v142, 16, v157
	v_and_b32_e32 v143, 0xffff0000, v157
	v_lshlrev_b32_e32 v144, 16, v158
	v_and_b32_e32 v145, 0xffff0000, v158
	v_lshlrev_b32_e32 v146, 16, v159
	v_and_b32_e32 v147, 0xffff0000, v159
	v_pk_mul_f32 v[130:131], v[102:103], s[60:61]
	v_pk_mul_f32 v[132:133], v[104:105], s[60:61]
	v_pk_mul_f32 v[134:135], v[94:95], s[60:61]
	v_pk_mul_f32 v[136:137], v[96:97], s[60:61]
	v_exp_f32_e32 v130, v130
	v_exp_f32_e32 v131, v131
	v_exp_f32_e32 v132, v132
	v_exp_f32_e32 v133, v133
	v_exp_f32_e32 v134, v134
	v_exp_f32_e32 v135, v135
	v_exp_f32_e32 v136, v136
	v_exp_f32_e32 v137, v137
	v_pk_add_f32 v[130:131], v[130:131], s[4:5]
	v_pk_add_f32 v[132:133], v[132:133], s[4:5]
	v_pk_add_f32 v[134:135], v[134:135], s[4:5]
	v_pk_add_f32 v[136:137], v[136:137], s[4:5]
	v_rcp_f32_e32 v130, v130
	v_rcp_f32_e32 v131, v131
	v_rcp_f32_e32 v132, v132
	v_rcp_f32_e32 v133, v133
	v_rcp_f32_e32 v134, v134
	v_rcp_f32_e32 v135, v135
	v_rcp_f32_e32 v136, v136
	v_rcp_f32_e32 v137, v137
	v_add_u32_e32 v140, 0x8000, v141
	v_pk_mul_f32 v[130:131], v[130:131], v[138:139]
	v_pk_mul_f32 v[132:133], v[132:133], v[142:143]
	v_pk_mul_f32 v[134:135], v[134:135], v[144:145]
	v_pk_mul_f32 v[136:137], v[136:137], v[146:147]
	v_cvt_pk_bf16_f32 v130, v130, v131
	v_cvt_pk_bf16_f32 v131, v132, v133
	v_cvt_pk_bf16_f32 v132, v134, v135
	v_cvt_pk_bf16_f32 v133, v136, v137
	global_store_dwordx4 v140, v[130:133], s[10:11]
	s_waitcnt vmcnt(16)
	v_lshlrev_b32_e32 v138, 16, v160
	v_and_b32_e32 v139, 0xffff0000, v160
	v_lshlrev_b32_e32 v142, 16, v161
	v_and_b32_e32 v143, 0xffff0000, v161
	v_lshlrev_b32_e32 v144, 16, v162
	v_and_b32_e32 v145, 0xffff0000, v162
	v_lshlrev_b32_e32 v146, 16, v163
	v_and_b32_e32 v147, 0xffff0000, v163
	v_pk_mul_f32 v[130:131], v[114:115], s[60:61]
	v_pk_mul_f32 v[132:133], v[116:117], s[60:61]
	v_pk_mul_f32 v[134:135], v[106:107], s[60:61]
	v_pk_mul_f32 v[136:137], v[108:109], s[60:61]
	v_exp_f32_e32 v130, v130
	v_exp_f32_e32 v131, v131
	v_exp_f32_e32 v132, v132
	v_exp_f32_e32 v133, v133
	v_exp_f32_e32 v134, v134
	v_exp_f32_e32 v135, v135
	v_exp_f32_e32 v136, v136
	v_exp_f32_e32 v137, v137
	v_pk_add_f32 v[130:131], v[130:131], s[4:5]
	v_pk_add_f32 v[132:133], v[132:133], s[4:5]
	v_pk_add_f32 v[134:135], v[134:135], s[4:5]
	v_pk_add_f32 v[136:137], v[136:137], s[4:5]
	v_rcp_f32_e32 v130, v130
	v_rcp_f32_e32 v131, v131
	v_rcp_f32_e32 v132, v132
	v_rcp_f32_e32 v133, v133
	v_rcp_f32_e32 v134, v134
	v_rcp_f32_e32 v135, v135
	v_rcp_f32_e32 v136, v136
	v_rcp_f32_e32 v137, v137
	v_add_u32_e32 v140, 0x8000, v141
	v_pk_mul_f32 v[130:131], v[130:131], v[138:139]
	v_pk_mul_f32 v[132:133], v[132:133], v[142:143]
	v_pk_mul_f32 v[134:135], v[134:135], v[144:145]
	v_pk_mul_f32 v[136:137], v[136:137], v[146:147]
	v_cvt_pk_bf16_f32 v130, v130, v131
	v_cvt_pk_bf16_f32 v131, v132, v133
	v_cvt_pk_bf16_f32 v132, v134, v135
	v_cvt_pk_bf16_f32 v133, v136, v137
	global_store_dwordx4 v140, v[130:133], s[10:11] offset:256
	s_waitcnt vmcnt(16)
; __device__ __forceinline__ unsigned pk2(float lo, float hi) { f32x2_t v = {lo, hi}; bf16x2_t b = __builtin_convertvector(v, bf16x2_t); return __builtin_bit_cast(unsigned, b); }
; __device__ __forceinline__ float bflo(unsigned u) { return __uint_as_float(u << 16); }
; __device__ __forceinline__ float bfhi(unsigned u) { return __uint_as_float(u & 0xffff0000u); }
; __device__ __forceinline__ float fast_sigmoid(float z) { return __builtin_amdgcn_rcpf(1.0f + __builtin_amdgcn_exp2f(-1.4426950408889634f * z)); }
;     __device__ __forceinline__ void operator()(const f32x4 (&acc)[2][2][4][2], const Unit& u, int wr, int wc, int fr, int fq) const {
;     ...
;                     if (mode == 1) {
;                         const u32x4 e = *(const u32x4*)(E + ro + bj * HALF);
;                         v0[0] = fast_sigmoid(v0[0]) * bflo(e.x); v0[1] = fast_sigmoid(v0[1]) * bfhi(e.x); v0[2] = fast_sigmoid(v0[2]) * bflo(e.y); v0[3] = fast_sigmoid(v0[3]) * bfhi(e.y);
;                         v1[0] = fast_sigmoid(v1[0]) * bflo(e.z); v1[1] = fast_sigmoid(v1[1]) * bfhi(e.z); v1[2] = fast_sigmoid(v1[2]) * bflo(e.w); v1[3] = fast_sigmoid(v1[3]) * bfhi(e.w);
;                     }
;                     u32x4 w; w.x = pk2(v0[0], v0[1]); w.y = pk2(v0[2], v0[3]); w.z = pk2(v1[0], v1[1]); w.w = pk2(v1[2], v1[3]);
;                     *(u32x4*)(O + ro + bj * HALF) = w;
	v_lshlrev_b32_e32 v138, 16, v164
	v_and_b32_e32 v139, 0xffff0000, v164
	v_lshlrev_b32_e32 v142, 16, v165
	v_and_b32_e32 v143, 0xffff0000, v165
	v_lshlrev_b32_e32 v144, 16, v166
	v_and_b32_e32 v145, 0xffff0000, v166
	v_lshlrev_b32_e32 v146, 16, v167
	v_and_b32_e32 v147, 0xffff0000, v167
	v_pk_mul_f32 v[130:131], v[86:87], s[60:61]
	v_pk_mul_f32 v[132:133], v[88:89], s[60:61]
	v_pk_mul_f32 v[134:135], v[74:75], s[60:61]
	v_pk_mul_f32 v[136:137], v[76:77], s[60:61]
	v_exp_f32_e32 v130, v130
	v_exp_f32_e32 v131, v131
	v_exp_f32_e32 v132, v132
	v_exp_f32_e32 v133, v133
	v_exp_f32_e32 v134, v134
	v_exp_f32_e32 v135, v135
	v_exp_f32_e32 v136, v136
	v_exp_f32_e32 v137, v137
	v_pk_add_f32 v[130:131], v[130:131], s[4:5]
	v_pk_add_f32 v[132:133], v[132:133], s[4:5]
	v_pk_add_f32 v[134:135], v[134:135], s[4:5]
	v_pk_add_f32 v[136:137], v[136:137], s[4:5]
	v_rcp_f32_e32 v130, v130
	v_rcp_f32_e32 v131, v131
	v_rcp_f32_e32 v132, v132
	v_rcp_f32_e32 v133, v133
	v_rcp_f32_e32 v134, v134
	v_rcp_f32_e32 v135, v135
	v_rcp_f32_e32 v136, v136
	v_rcp_f32_e32 v137, v137
	v_add_u32_e32 v140, 0x10000, v141
	v_pk_mul_f32 v[130:131], v[130:131], v[138:139]
	v_pk_mul_f32 v[132:133], v[132:133], v[142:143]
	v_pk_mul_f32 v[134:135], v[134:135], v[144:145]
	v_pk_mul_f32 v[136:137], v[136:137], v[146:147]
	v_cvt_pk_bf16_f32 v130, v130, v131
	v_cvt_pk_bf16_f32 v131, v132, v133
	v_cvt_pk_bf16_f32 v132, v134, v135
	v_cvt_pk_bf16_f32 v133, v136, v137
	global_store_dwordx4 v140, v[130:133], s[10:11]
	s_waitcnt vmcnt(16)
	v_lshlrev_b32_e32 v138, 16, v168
	v_and_b32_e32 v139, 0xffff0000, v168
	v_lshlrev_b32_e32 v142, 16, v169
	v_and_b32_e32 v143, 0xffff0000, v169
	v_lshlrev_b32_e32 v144, 16, v170
	v_and_b32_e32 v145, 0xffff0000, v170
	v_lshlrev_b32_e32 v146, 16, v171
	v_and_b32_e32 v147, 0xffff0000, v171
	v_pk_mul_f32 v[130:131], v[98:99], s[60:61]
	v_pk_mul_f32 v[132:133], v[100:101], s[60:61]
	v_pk_mul_f32 v[134:135], v[90:91], s[60:61]
	v_pk_mul_f32 v[136:137], v[92:93], s[60:61]
	v_exp_f32_e32 v130, v130
	v_exp_f32_e32 v131, v131
	v_exp_f32_e32 v132, v132
	v_exp_f32_e32 v133, v133
	v_exp_f32_e32 v134, v134
	v_exp_f32_e32 v135, v135
	v_exp_f32_e32 v136, v136
	v_exp_f32_e32 v137, v137
	v_pk_add_f32 v[130:131], v[130:131], s[4:5]
	v_pk_add_f32 v[132:133], v[132:133], s[4:5]
	v_pk_add_f32 v[134:135], v[134:135], s[4:5]
	v_pk_add_f32 v[136:137], v[136:137], s[4:5]
	v_rcp_f32_e32 v130, v130
	v_rcp_f32_e32 v131, v131
	v_rcp_f32_e32 v132, v132
	v_rcp_f32_e32 v133, v133
	v_rcp_f32_e32 v134, v134
	v_rcp_f32_e32 v135, v135
	v_rcp_f32_e32 v136, v136
	v_rcp_f32_e32 v137, v137
	v_add_u32_e32 v140, 0x10000, v141
	v_pk_mul_f32 v[130:131], v[130:131], v[138:139]
	v_pk_mul_f32 v[132:133], v[132:133], v[142:143]
	v_pk_mul_f32 v[134:135], v[134:135], v[144:145]
	v_pk_mul_f32 v[136:137], v[136:137], v[146:147]
	v_cvt_pk_bf16_f32 v130, v130, v131
	v_cvt_pk_bf16_f32 v131, v132, v133
	v_cvt_pk_bf16_f32 v132, v134, v135
	v_cvt_pk_bf16_f32 v133, v136, v137
	global_store_dwordx4 v140, v[130:133], s[10:11] offset:256
	s_waitcnt vmcnt(16)
	v_lshlrev_b32_e32 v138, 16, v172
	v_and_b32_e32 v139, 0xffff0000, v172
	v_lshlrev_b32_e32 v142, 16, v173
	v_and_b32_e32 v143, 0xffff0000, v173
	v_lshlrev_b32_e32 v144, 16, v174
	v_and_b32_e32 v145, 0xffff0000, v174
	v_lshlrev_b32_e32 v146, 16, v175
	v_and_b32_e32 v147, 0xffff0000, v175
	v_pk_mul_f32 v[130:131], v[82:83], s[60:61]
	v_pk_mul_f32 v[132:133], v[84:85], s[60:61]
	v_pk_mul_f32 v[134:135], v[70:71], s[60:61]
	v_pk_mul_f32 v[136:137], v[72:73], s[60:61]
	v_exp_f32_e32 v130, v130
	v_exp_f32_e32 v131, v131
	v_exp_f32_e32 v132, v132
	v_exp_f32_e32 v133, v133
	v_exp_f32_e32 v134, v134
	v_exp_f32_e32 v135, v135
	v_exp_f32_e32 v136, v136
	v_exp_f32_e32 v137, v137
	v_pk_add_f32 v[130:131], v[130:131], s[4:5]
	v_pk_add_f32 v[132:133], v[132:133], s[4:5]
	v_pk_add_f32 v[134:135], v[134:135], s[4:5]
	v_pk_add_f32 v[136:137], v[136:137], s[4:5]
	v_rcp_f32_e32 v130, v130
	v_rcp_f32_e32 v131, v131
	v_rcp_f32_e32 v132, v132
	v_rcp_f32_e32 v133, v133
	v_rcp_f32_e32 v134, v134
	v_rcp_f32_e32 v135, v135
	v_rcp_f32_e32 v136, v136
	v_rcp_f32_e32 v137, v137
	v_add_u32_e32 v140, 0x18000, v141
	v_pk_mul_f32 v[130:131], v[130:131], v[138:139]
	v_pk_mul_f32 v[132:133], v[132:133], v[142:143]
	v_pk_mul_f32 v[134:135], v[134:135], v[144:145]
	v_pk_mul_f32 v[136:137], v[136:137], v[146:147]
	v_cvt_pk_bf16_f32 v130, v130, v131
	v_cvt_pk_bf16_f32 v131, v132, v133
	v_cvt_pk_bf16_f32 v132, v134, v135
	v_cvt_pk_bf16_f32 v133, v136, v137
	global_store_dwordx4 v140, v[130:133], s[10:11]
	s_waitcnt vmcnt(16)
	v_lshlrev_b32_e32 v138, 16, v220
	v_and_b32_e32 v139, 0xffff0000, v220
	v_lshlrev_b32_e32 v142, 16, v221
	v_and_b32_e32 v143, 0xffff0000, v221
	v_lshlrev_b32_e32 v144, 16, v222
	v_and_b32_e32 v145, 0xffff0000, v222
	v_lshlrev_b32_e32 v146, 16, v223
	v_and_b32_e32 v147, 0xffff0000, v223
	v_pk_mul_f32 v[130:131], v[78:79], s[60:61]
	v_pk_mul_f32 v[132:133], v[80:81], s[60:61]
	v_pk_mul_f32 v[134:135], v[66:67], s[60:61]
	v_pk_mul_f32 v[136:137], v[68:69], s[60:61]
	v_exp_f32_e32 v130, v130
	v_exp_f32_e32 v131, v131
	v_exp_f32_e32 v132, v132
	v_exp_f32_e32 v133, v133
	v_exp_f32_e32 v134, v134
	v_exp_f32_e32 v135, v135
	v_exp_f32_e32 v136, v136
	v_exp_f32_e32 v137, v137
	v_pk_add_f32 v[130:131], v[130:131], s[4:5]
	v_pk_add_f32 v[132:133], v[132:133], s[4:5]
	v_pk_add_f32 v[134:135], v[134:135], s[4:5]
	v_pk_add_f32 v[136:137], v[136:137], s[4:5]
	v_rcp_f32_e32 v130, v130
	v_rcp_f32_e32 v131, v131
	v_rcp_f32_e32 v132, v132
	v_rcp_f32_e32 v133, v133
	v_rcp_f32_e32 v134, v134
	v_rcp_f32_e32 v135, v135
	v_rcp_f32_e32 v136, v136
	v_rcp_f32_e32 v137, v137
	v_add_u32_e32 v140, 0x18000, v141
	v_pk_mul_f32 v[130:131], v[130:131], v[138:139]
	v_pk_mul_f32 v[132:133], v[132:133], v[142:143]
	v_pk_mul_f32 v[134:135], v[134:135], v[144:145]
	v_pk_mul_f32 v[136:137], v[136:137], v[146:147]
	v_cvt_pk_bf16_f32 v130, v130, v131
	v_cvt_pk_bf16_f32 v131, v132, v133
	v_cvt_pk_bf16_f32 v132, v134, v135
	v_cvt_pk_bf16_f32 v133, v136, v137
	global_store_dwordx4 v140, v[130:133], s[10:11] offset:256
	s_waitcnt vmcnt(16)
; __device__ __forceinline__ unsigned pk2(float lo, float hi) { f32x2_t v = {lo, hi}; bf16x2_t b = __builtin_convertvector(v, bf16x2_t); return __builtin_bit_cast(unsigned, b); }
; __device__ __forceinline__ float bflo(unsigned u) { return __uint_as_float(u << 16); }
; __device__ __forceinline__ float bfhi(unsigned u) { return __uint_as_float(u & 0xffff0000u); }
; __device__ __forceinline__ float fast_sigmoid(float z) { return __builtin_amdgcn_rcpf(1.0f + __builtin_amdgcn_exp2f(-1.4426950408889634f * z)); }
;     __device__ __forceinline__ void operator()(const f32x4 (&acc)[2][2][4][2], const Unit& u, int wr, int wc, int fr, int fq) const {
;     ...
;                     if (mode == 1) {
;                         const u32x4 e = *(const u32x4*)(E + ro + bj * HALF);
;                         v0[0] = fast_sigmoid(v0[0]) * bflo(e.x); v0[1] = fast_sigmoid(v0[1]) * bfhi(e.x); v0[2] = fast_sigmoid(v0[2]) * bflo(e.y); v0[3] = fast_sigmoid(v0[3]) * bfhi(e.y);
;                         v1[0] = fast_sigmoid(v1[0]) * bflo(e.z); v1[1] = fast_sigmoid(v1[1]) * bfhi(e.z); v1[2] = fast_sigmoid(v1[2]) * bflo(e.w); v1[3] = fast_sigmoid(v1[3]) * bfhi(e.w);
;                     }
;                     u32x4 w; w.x = pk2(v0[0], v0[1]); w.y = pk2(v0[2], v0[3]); w.z = pk2(v1[0], v1[1]); w.w = pk2(v1[2], v1[3]);
;                     *(u32x4*)(O + ro + bj * HALF) = w;
	v_lshlrev_b32_e32 v138, 16, v224
	v_and_b32_e32 v139, 0xffff0000, v224
	v_lshlrev_b32_e32 v142, 16, v225
	v_and_b32_e32 v143, 0xffff0000, v225
	v_lshlrev_b32_e32 v144, 16, v226
	v_and_b32_e32 v145, 0xffff0000, v226
	v_lshlrev_b32_e32 v146, 16, v227
	v_and_b32_e32 v147, 0xffff0000, v227
	v_pk_mul_f32 v[130:131], v[54:55], s[60:61]
	v_pk_mul_f32 v[132:133], v[56:57], s[60:61]
	v_pk_mul_f32 v[134:135], v[46:47], s[60:61]
	v_pk_mul_f32 v[136:137], v[48:49], s[60:61]
	v_exp_f32_e32 v130, v130
	v_exp_f32_e32 v131, v131
	v_exp_f32_e32 v132, v132
	v_exp_f32_e32 v133, v133
	v_exp_f32_e32 v134, v134
	v_exp_f32_e32 v135, v135
	v_exp_f32_e32 v136, v136
	v_exp_f32_e32 v137, v137
	v_pk_add_f32 v[130:131], v[130:131], s[4:5]
	v_pk_add_f32 v[132:133], v[132:133], s[4:5]
	v_pk_add_f32 v[134:135], v[134:135], s[4:5]
	v_pk_add_f32 v[136:137], v[136:137], s[4:5]
	v_rcp_f32_e32 v130, v130
	v_rcp_f32_e32 v131, v131
	v_rcp_f32_e32 v132, v132
	v_rcp_f32_e32 v133, v133
	v_rcp_f32_e32 v134, v134
	v_rcp_f32_e32 v135, v135
	v_rcp_f32_e32 v136, v136
	v_rcp_f32_e32 v137, v137
	v_add_u32_e32 v140, 0x40000, v141
	v_pk_mul_f32 v[130:131], v[130:131], v[138:139]
	v_pk_mul_f32 v[132:133], v[132:133], v[142:143]
	v_pk_mul_f32 v[134:135], v[134:135], v[144:145]
	v_pk_mul_f32 v[136:137], v[136:137], v[146:147]
	v_cvt_pk_bf16_f32 v130, v130, v131
	v_cvt_pk_bf16_f32 v131, v132, v133
	v_cvt_pk_bf16_f32 v132, v134, v135
	v_cvt_pk_bf16_f32 v133, v136, v137
	global_store_dwordx4 v140, v[130:133], s[10:11]
	s_waitcnt vmcnt(16)
	v_lshlrev_b32_e32 v138, 16, v228
	v_and_b32_e32 v139, 0xffff0000, v228
	v_lshlrev_b32_e32 v142, 16, v229
	v_and_b32_e32 v143, 0xffff0000, v229
	v_lshlrev_b32_e32 v144, 16, v230
	v_and_b32_e32 v145, 0xffff0000, v230
	v_lshlrev_b32_e32 v146, 16, v231
	v_and_b32_e32 v147, 0xffff0000, v231
	v_pk_mul_f32 v[130:131], v[62:63], s[60:61]
	v_pk_mul_f32 v[132:133], v[64:65], s[60:61]
	v_pk_mul_f32 v[134:135], v[58:59], s[60:61]
	v_pk_mul_f32 v[136:137], v[60:61], s[60:61]
	v_exp_f32_e32 v130, v130
	v_exp_f32_e32 v131, v131
	v_exp_f32_e32 v132, v132
	v_exp_f32_e32 v133, v133
	v_exp_f32_e32 v134, v134
	v_exp_f32_e32 v135, v135
	v_exp_f32_e32 v136, v136
	v_exp_f32_e32 v137, v137
	v_pk_add_f32 v[130:131], v[130:131], s[4:5]
	v_pk_add_f32 v[132:133], v[132:133], s[4:5]
	v_pk_add_f32 v[134:135], v[134:135], s[4:5]
	v_pk_add_f32 v[136:137], v[136:137], s[4:5]
	v_rcp_f32_e32 v130, v130
	v_rcp_f32_e32 v131, v131
	v_rcp_f32_e32 v132, v132
	v_rcp_f32_e32 v133, v133
	v_rcp_f32_e32 v134, v134
	v_rcp_f32_e32 v135, v135
	v_rcp_f32_e32 v136, v136
	v_rcp_f32_e32 v137, v137
	v_add_u32_e32 v140, 0x40000, v141
	v_pk_mul_f32 v[130:131], v[130:131], v[138:139]
	v_pk_mul_f32 v[132:133], v[132:133], v[142:143]
	v_pk_mul_f32 v[134:135], v[134:135], v[144:145]
	v_pk_mul_f32 v[136:137], v[136:137], v[146:147]
	v_cvt_pk_bf16_f32 v130, v130, v131
	v_cvt_pk_bf16_f32 v131, v132, v133
	v_cvt_pk_bf16_f32 v132, v134, v135
	v_cvt_pk_bf16_f32 v133, v136, v137
	global_store_dwordx4 v140, v[130:133], s[10:11] offset:256
	s_waitcnt vmcnt(16)
	v_lshlrev_b32_e32 v138, 16, v232
	v_and_b32_e32 v139, 0xffff0000, v232
	v_lshlrev_b32_e32 v142, 16, v233
	v_and_b32_e32 v143, 0xffff0000, v233
	v_lshlrev_b32_e32 v144, 16, v234
	v_and_b32_e32 v145, 0xffff0000, v234
	v_lshlrev_b32_e32 v146, 16, v235
	v_and_b32_e32 v147, 0xffff0000, v235
	v_pk_mul_f32 v[130:131], v[38:39], s[60:61]
	v_pk_mul_f32 v[132:133], v[40:41], s[60:61]
	v_pk_mul_f32 v[134:135], v[30:31], s[60:61]
	v_pk_mul_f32 v[136:137], v[32:33], s[60:61]
	v_exp_f32_e32 v130, v130
	v_exp_f32_e32 v131, v131
	v_exp_f32_e32 v132, v132
	v_exp_f32_e32 v133, v133
	v_exp_f32_e32 v134, v134
	v_exp_f32_e32 v135, v135
	v_exp_f32_e32 v136, v136
	v_exp_f32_e32 v137, v137
	v_pk_add_f32 v[130:131], v[130:131], s[4:5]
	v_pk_add_f32 v[132:133], v[132:133], s[4:5]
	v_pk_add_f32 v[134:135], v[134:135], s[4:5]
	v_pk_add_f32 v[136:137], v[136:137], s[4:5]
	v_rcp_f32_e32 v130, v130
	v_rcp_f32_e32 v131, v131
	v_rcp_f32_e32 v132, v132
	v_rcp_f32_e32 v133, v133
	v_rcp_f32_e32 v134, v134
	v_rcp_f32_e32 v135, v135
	v_rcp_f32_e32 v136, v136
	v_rcp_f32_e32 v137, v137
	v_add_u32_e32 v140, 0x48000, v141
	v_pk_mul_f32 v[130:131], v[130:131], v[138:139]
	v_pk_mul_f32 v[132:133], v[132:133], v[142:143]
	v_pk_mul_f32 v[134:135], v[134:135], v[144:145]
	v_pk_mul_f32 v[136:137], v[136:137], v[146:147]
	v_cvt_pk_bf16_f32 v130, v130, v131
	v_cvt_pk_bf16_f32 v131, v132, v133
	v_cvt_pk_bf16_f32 v132, v134, v135
	v_cvt_pk_bf16_f32 v133, v136, v137
	global_store_dwordx4 v140, v[130:133], s[10:11]
	s_waitcnt vmcnt(16)
	v_lshlrev_b32_e32 v138, 16, v236
	v_and_b32_e32 v139, 0xffff0000, v236
	v_lshlrev_b32_e32 v142, 16, v237
	v_and_b32_e32 v143, 0xffff0000, v237
	v_lshlrev_b32_e32 v144, 16, v238
	v_and_b32_e32 v145, 0xffff0000, v238
	v_lshlrev_b32_e32 v146, 16, v239
	v_and_b32_e32 v147, 0xffff0000, v239
	v_pk_mul_f32 v[130:131], v[50:51], s[60:61]
	v_pk_mul_f32 v[132:133], v[52:53], s[60:61]
	v_pk_mul_f32 v[134:135], v[42:43], s[60:61]
	v_pk_mul_f32 v[136:137], v[44:45], s[60:61]
	v_exp_f32_e32 v130, v130
	v_exp_f32_e32 v131, v131
	v_exp_f32_e32 v132, v132
	v_exp_f32_e32 v133, v133
	v_exp_f32_e32 v134, v134
	v_exp_f32_e32 v135, v135
	v_exp_f32_e32 v136, v136
	v_exp_f32_e32 v137, v137
	v_pk_add_f32 v[130:131], v[130:131], s[4:5]
	v_pk_add_f32 v[132:133], v[132:133], s[4:5]
	v_pk_add_f32 v[134:135], v[134:135], s[4:5]
	v_pk_add_f32 v[136:137], v[136:137], s[4:5]
	v_rcp_f32_e32 v130, v130
	v_rcp_f32_e32 v131, v131
	v_rcp_f32_e32 v132, v132
	v_rcp_f32_e32 v133, v133
	v_rcp_f32_e32 v134, v134
	v_rcp_f32_e32 v135, v135
	v_rcp_f32_e32 v136, v136
	v_rcp_f32_e32 v137, v137
	v_add_u32_e32 v140, 0x48000, v141
	v_pk_mul_f32 v[130:131], v[130:131], v[138:139]
	v_pk_mul_f32 v[132:133], v[132:133], v[142:143]
	v_pk_mul_f32 v[134:135], v[134:135], v[144:145]
	v_pk_mul_f32 v[136:137], v[136:137], v[146:147]
	v_cvt_pk_bf16_f32 v130, v130, v131
	v_cvt_pk_bf16_f32 v131, v132, v133
	v_cvt_pk_bf16_f32 v132, v134, v135
	v_cvt_pk_bf16_f32 v133, v136, v137
	global_store_dwordx4 v140, v[130:133], s[10:11] offset:256
	s_waitcnt vmcnt(16)
; __device__ __forceinline__ unsigned pk2(float lo, float hi) { f32x2_t v = {lo, hi}; bf16x2_t b = __builtin_convertvector(v, bf16x2_t); return __builtin_bit_cast(unsigned, b); }
; __device__ __forceinline__ float bflo(unsigned u) { return __uint_as_float(u << 16); }
; __device__ __forceinline__ float bfhi(unsigned u) { return __uint_as_float(u & 0xffff0000u); }
; __device__ __forceinline__ float fast_sigmoid(float z) { return __builtin_amdgcn_rcpf(1.0f + __builtin_amdgcn_exp2f(-1.4426950408889634f * z)); }
;     __device__ __forceinline__ void operator()(const f32x4 (&acc)[2][2][4][2], const Unit& u, int wr, int wc, int fr, int fq) const {
;     ...
;                     if (mode == 1) {
;                         const u32x4 e = *(const u32x4*)(E + ro + bj * HALF);
;                         v0[0] = fast_sigmoid(v0[0]) * bflo(e.x); v0[1] = fast_sigmoid(v0[1]) * bfhi(e.x); v0[2] = fast_sigmoid(v0[2]) * bflo(e.y); v0[3] = fast_sigmoid(v0[3]) * bfhi(e.y);
;                         v1[0] = fast_sigmoid(v1[0]) * bflo(e.z); v1[1] = fast_sigmoid(v1[1]) * bfhi(e.z); v1[2] = fast_sigmoid(v1[2]) * bflo(e.w); v1[3] = fast_sigmoid(v1[3]) * bfhi(e.w);
;                     }
;                     u32x4 w; w.x = pk2(v0[0], v0[1]); w.y = pk2(v0[2], v0[3]); w.z = pk2(v1[0], v1[1]); w.w = pk2(v1[2], v1[3]);
;                     *(u32x4*)(O + ro + bj * HALF) = w;
	v_lshlrev_b32_e32 v138, 16, v240
	v_and_b32_e32 v139, 0xffff0000, v240
	v_lshlrev_b32_e32 v142, 16, v241
	v_and_b32_e32 v143, 0xffff0000, v241
	v_lshlrev_b32_e32 v144, 16, v242
	v_and_b32_e32 v145, 0xffff0000, v242
	v_lshlrev_b32_e32 v146, 16, v243
	v_and_b32_e32 v147, 0xffff0000, v243
	v_pk_mul_f32 v[130:131], v[22:23], s[60:61]
	v_pk_mul_f32 v[132:133], v[24:25], s[60:61]
	v_pk_mul_f32 v[134:135], v[18:19], s[60:61]
	v_pk_mul_f32 v[136:137], v[20:21], s[60:61]
	v_exp_f32_e32 v130, v130
	v_exp_f32_e32 v131, v131
	v_exp_f32_e32 v132, v132
	v_exp_f32_e32 v133, v133
	v_exp_f32_e32 v134, v134
	v_exp_f32_e32 v135, v135
	v_exp_f32_e32 v136, v136
	v_exp_f32_e32 v137, v137
	v_pk_add_f32 v[130:131], v[130:131], s[4:5]
	v_pk_add_f32 v[132:133], v[132:133], s[4:5]
	v_pk_add_f32 v[134:135], v[134:135], s[4:5]
	v_pk_add_f32 v[136:137], v[136:137], s[4:5]
	v_rcp_f32_e32 v130, v130
	v_rcp_f32_e32 v131, v131
	v_rcp_f32_e32 v132, v132
	v_rcp_f32_e32 v133, v133
	v_rcp_f32_e32 v134, v134
	v_rcp_f32_e32 v135, v135
	v_rcp_f32_e32 v136, v136
	v_rcp_f32_e32 v137, v137
	v_add_u32_e32 v140, 0x50000, v141
	v_pk_mul_f32 v[130:131], v[130:131], v[138:139]
	v_pk_mul_f32 v[132:133], v[132:133], v[142:143]
	v_pk_mul_f32 v[134:135], v[134:135], v[144:145]
	v_pk_mul_f32 v[136:137], v[136:137], v[146:147]
	v_cvt_pk_bf16_f32 v130, v130, v131
	v_cvt_pk_bf16_f32 v131, v132, v133
	v_cvt_pk_bf16_f32 v132, v134, v135
	v_cvt_pk_bf16_f32 v133, v136, v137
	global_store_dwordx4 v140, v[130:133], s[10:11]
	s_waitcnt vmcnt(16)
	v_lshlrev_b32_e32 v138, 16, v244
	v_and_b32_e32 v139, 0xffff0000, v244
	v_lshlrev_b32_e32 v142, 16, v245
	v_and_b32_e32 v143, 0xffff0000, v245
	v_lshlrev_b32_e32 v144, 16, v246
	v_and_b32_e32 v145, 0xffff0000, v246
	v_lshlrev_b32_e32 v146, 16, v247
	v_and_b32_e32 v147, 0xffff0000, v247
	v_pk_mul_f32 v[130:131], v[34:35], s[60:61]
	v_pk_mul_f32 v[132:133], v[36:37], s[60:61]
	v_pk_mul_f32 v[134:135], v[26:27], s[60:61]
	v_pk_mul_f32 v[136:137], v[28:29], s[60:61]
	v_exp_f32_e32 v130, v130
	v_exp_f32_e32 v131, v131
	v_exp_f32_e32 v132, v132
	v_exp_f32_e32 v133, v133
	v_exp_f32_e32 v134, v134
	v_exp_f32_e32 v135, v135
	v_exp_f32_e32 v136, v136
	v_exp_f32_e32 v137, v137
	v_pk_add_f32 v[130:131], v[130:131], s[4:5]
	v_pk_add_f32 v[132:133], v[132:133], s[4:5]
	v_pk_add_f32 v[134:135], v[134:135], s[4:5]
	v_pk_add_f32 v[136:137], v[136:137], s[4:5]
	v_rcp_f32_e32 v130, v130
	v_rcp_f32_e32 v131, v131
	v_rcp_f32_e32 v132, v132
	v_rcp_f32_e32 v133, v133
	v_rcp_f32_e32 v134, v134
	v_rcp_f32_e32 v135, v135
	v_rcp_f32_e32 v136, v136
	v_rcp_f32_e32 v137, v137
	v_add_u32_e32 v140, 0x50000, v141
	v_pk_mul_f32 v[130:131], v[130:131], v[138:139]
	v_pk_mul_f32 v[132:133], v[132:133], v[142:143]
	v_pk_mul_f32 v[134:135], v[134:135], v[144:145]
	v_pk_mul_f32 v[136:137], v[136:137], v[146:147]
	v_cvt_pk_bf16_f32 v130, v130, v131
	v_cvt_pk_bf16_f32 v131, v132, v133
	v_cvt_pk_bf16_f32 v132, v134, v135
	v_cvt_pk_bf16_f32 v133, v136, v137
	global_store_dwordx4 v140, v[130:133], s[10:11] offset:256
	s_waitcnt vmcnt(16)
	v_lshlrev_b32_e32 v138, 16, v248
	v_and_b32_e32 v139, 0xffff0000, v248
	v_lshlrev_b32_e32 v142, 16, v249
	v_and_b32_e32 v143, 0xffff0000, v249
	v_lshlrev_b32_e32 v144, 16, v250
	v_and_b32_e32 v145, 0xffff0000, v250
	v_lshlrev_b32_e32 v146, 16, v251
	v_and_b32_e32 v147, 0xffff0000, v251
	v_pk_mul_f32 v[130:131], v[14:15], s[60:61]
	v_pk_mul_f32 v[132:133], v[16:17], s[60:61]
	v_pk_mul_f32 v[134:135], v[6:7], s[60:61]
	v_pk_mul_f32 v[136:137], v[8:9], s[60:61]
	v_exp_f32_e32 v130, v130
	v_exp_f32_e32 v131, v131
	v_exp_f32_e32 v132, v132
	v_exp_f32_e32 v133, v133
	v_exp_f32_e32 v134, v134
	v_exp_f32_e32 v135, v135
	v_exp_f32_e32 v136, v136
	v_exp_f32_e32 v137, v137
	v_pk_add_f32 v[130:131], v[130:131], s[4:5]
	v_pk_add_f32 v[132:133], v[132:133], s[4:5]
	v_pk_add_f32 v[134:135], v[134:135], s[4:5]
	v_pk_add_f32 v[136:137], v[136:137], s[4:5]
	v_rcp_f32_e32 v130, v130
	v_rcp_f32_e32 v131, v131
	v_rcp_f32_e32 v132, v132
	v_rcp_f32_e32 v133, v133
	v_rcp_f32_e32 v134, v134
	v_rcp_f32_e32 v135, v135
	v_rcp_f32_e32 v136, v136
	v_rcp_f32_e32 v137, v137
	v_add_u32_e32 v140, 0x58000, v141
	v_pk_mul_f32 v[130:131], v[130:131], v[138:139]
	v_pk_mul_f32 v[132:133], v[132:133], v[142:143]
	v_pk_mul_f32 v[134:135], v[134:135], v[144:145]
	v_pk_mul_f32 v[136:137], v[136:137], v[146:147]
	v_cvt_pk_bf16_f32 v130, v130, v131
	v_cvt_pk_bf16_f32 v131, v132, v133
	v_cvt_pk_bf16_f32 v132, v134, v135
	v_cvt_pk_bf16_f32 v133, v136, v137
	global_store_dwordx4 v140, v[130:133], s[10:11]
	s_waitcnt vmcnt(15)
	v_lshlrev_b32_e32 v138, 16, v176
	v_and_b32_e32 v139, 0xffff0000, v176
	v_lshlrev_b32_e32 v142, 16, v177
	v_and_b32_e32 v143, 0xffff0000, v177
	v_lshlrev_b32_e32 v144, 16, v188
	v_and_b32_e32 v145, 0xffff0000, v188
	v_lshlrev_b32_e32 v146, 16, v189
	v_and_b32_e32 v147, 0xffff0000, v189
	v_pk_mul_f32 v[130:131], v[10:11], s[60:61]
	v_pk_mul_f32 v[132:133], v[12:13], s[60:61]
	v_pk_mul_f32 v[134:135], v[2:3], s[60:61]
	v_pk_mul_f32 v[136:137], v[4:5], s[60:61]
	v_exp_f32_e32 v130, v130
	v_exp_f32_e32 v131, v131
	v_exp_f32_e32 v132, v132
	v_exp_f32_e32 v133, v133
	v_exp_f32_e32 v134, v134
	v_exp_f32_e32 v135, v135
	v_exp_f32_e32 v136, v136
	v_exp_f32_e32 v137, v137
	v_pk_add_f32 v[130:131], v[130:131], s[4:5]
	v_pk_add_f32 v[132:133], v[132:133], s[4:5]
	v_pk_add_f32 v[134:135], v[134:135], s[4:5]
	v_pk_add_f32 v[136:137], v[136:137], s[4:5]
	v_rcp_f32_e32 v130, v130
	v_rcp_f32_e32 v131, v131
	v_rcp_f32_e32 v132, v132
	v_rcp_f32_e32 v133, v133
	v_rcp_f32_e32 v134, v134
	v_rcp_f32_e32 v135, v135
	v_rcp_f32_e32 v136, v136
	v_rcp_f32_e32 v137, v137
	v_add_u32_e32 v140, 0x58000, v141
	v_pk_mul_f32 v[130:131], v[130:131], v[138:139]
	v_pk_mul_f32 v[132:133], v[132:133], v[142:143]
	v_pk_mul_f32 v[134:135], v[134:135], v[144:145]
	v_pk_mul_f32 v[136:137], v[136:137], v[146:147]
	v_cvt_pk_bf16_f32 v130, v130, v131
	v_cvt_pk_bf16_f32 v131, v132, v133
	v_cvt_pk_bf16_f32 v132, v134, v135
	v_cvt_pk_bf16_f32 v133, v136, v137
	global_store_dwordx4 v140, v[130:133], s[10:11] offset:256
	s_branch .LBB0_535
